# last layer: final rmsnorm folded into phase 6 (y kept in accumulators across the grid barrier, per-row sums of squares exchanged through LDS + workspace, output stored once)
# speedup vs baseline: 1.0300x; 1.0127x over previous
; #define PG8_STAGE(bufoff, gbase, voff) do { _Pragma("unroll") for (int _i = 0; _i < 2; ++_i) \
;         __builtin_amdgcn_global_load_lds((const unsigned*)((const char*)(gbase) + (voff)[_i]), (LAS unsigned*)(lds + (bufoff) + ldsw + _i * 8192), 16, 0, 0); } while (0)
; #define PG8_LDA(dst, b, h) do { _Pragma("unroll") for (int m = 0; m < 4; ++m) _Pragma("unroll") for (int k = 0; k < 2; ++k) dst[m][k] = *(const LAS bf16x8*)(lds + PG8_SA(b, h) + aoff + m * 2048 + k * 1024); } while (0)
; #define PG8_WAIT_V(n) asm volatile("s_waitcnt vmcnt(" #n ")" ::: "memory")
; #define PG8_BAR __builtin_amdgcn_s_barrier()
; template <class Epi, class Sched>
; DI void gemm_phase(LAS unsigned char* lds, const Gemm g, const Sched& S, const Epi& E) {
;     ...
;         for (int t = 0; t < nt; t += 2) {
;             const bool last = (t == nt - 2);
;             const char* a1 = cA + (size_t)(t + 1) * kstep;
;             const char* a2 = last ? nA : cA + (size_t)(t + 2) * kstep; const char* b2 = last ? nB : cB + (size_t)(t + 2) * kstep;
;             const char* a3 = a2 + kstep; const char* b3 = b2 + kstep;
;             if (last && has_next) S.a_ready(nxt);
;             PG8_LDB(B0, 0, 0); PG8_SCHED; PG8_LDA(At, 0, 0); PG8_STAGE(PG8_SA(1, 1), a1 + hstepA, voffA);
;             PG8_WAIT_L(8); PG8_BAR; PG8_WAIT_L(0); PG8_MMA(0, 0, At, B0); PG8_BAR; PG8_SCHED;
;             PG8_LDB(B1, 0, 1); PG8_STAGE(PG8_SB(0, 0), b2, voffB);
;             PG8_BAR; PG8_WAIT_L(0); PG8_MMA(0, 1, At, B1); PG8_BAR;
;             PG8_LDA(At, 0, 1); PG8_STAGE(PG8_SA(0, 0), a2, voffA);
;             PG8_BAR; PG8_WAIT_L(0); PG8_MMA(1, 0, At, B0); PG8_BAR; PG8_SCHED;
;             PG8_STAGE(PG8_SB(0, 1), b2 + hstepB, voffB);
;             PG8_WAIT_V(6); PG8_BAR; PG8_MMA(1, 1, At, B1); PG8_BAR;
;             PG8_LDB(B0, 1, 0); PG8_SCHED; PG8_LDA(At, 1, 0); PG8_STAGE(PG8_SA(0, 1), a2 + hstepA, voffA);
;             PG8_WAIT_L(8); PG8_BAR; PG8_WAIT_L(0); PG8_MMA(0, 0, At, B0); PG8_BAR; PG8_SCHED;
;             PG8_LDB(B1, 1, 1); PG8_STAGE(PG8_SB(1, 0), b3, voffB);
;             PG8_BAR; PG8_WAIT_L(0); PG8_MMA(0, 1, At, B1); PG8_BAR;
;             PG8_LDA(At, 1, 1); PG8_STAGE(PG8_SA(1, 0), a3, voffA);
;             PG8_BAR; PG8_WAIT_L(0); PG8_MMA(1, 0, At, B0); PG8_BAR; PG8_SCHED;
;             PG8_STAGE(PG8_SB(1, 1), b3 + hstepB, voffB);
;             PG8_WAIT_V(6); PG8_BAR; PG8_MMA(1, 1, At, B1); PG8_BAR;
.LBB0_1039:
	s_add_u32 s0, s42, 0xfffc0080
	s_addc_u32 s1, s43, -1
	s_add_i32 s11, 0, 0x10000
	s_cmp_eq_u32 s60, 12
	s_cselect_b32 s47, s6, s1
	s_cselect_b32 s46, s7, s0
	s_cselect_b32 s45, s9, s59
	s_cselect_b32 s44, s13, s58
	v_lshl_add_u64 v[188:189], s[42:43], 0, v[134:135]
	s_add_i32 m0, s51, 0xc000
	ds_read_b128 v[156:159], v147
	ds_read_b128 v[160:163], v147 offset:1024
	ds_read_b128 v[164:167], v147 offset:2048
	ds_read_b128 v[168:171], v147 offset:3072
	ds_read_b128 v[172:175], v147 offset:4096
	ds_read_b128 v[176:179], v147 offset:5120
	ds_read_b128 v[180:183], v147 offset:6144
	ds_read_b128 v[184:187], v147 offset:7168
	global_load_lds_dwordx4 v[188:189], off
	v_lshl_add_u64 v[188:189], s[42:43], 0, v[132:133]
	s_add_i32 m0, s51, 0xe000
	s_nop 0
	global_load_lds_dwordx4 v[188:189], off
	s_waitcnt lgkmcnt(8)
	s_barrier
	s_waitcnt lgkmcnt(0)
	s_setprio 1
	s_waitcnt lgkmcnt(0)
	v_mfma_f32_16x16x32_bf16 v[126:129], v[136:139], v[156:159], v[126:129]
	v_mfma_f32_16x16x32_bf16 v[122:125], v[148:151], v[156:159], v[122:125]
	v_mfma_f32_16x16x32_bf16 v[118:121], v[136:139], v[164:167], v[118:121]
	v_mfma_f32_16x16x32_bf16 v[114:117], v[148:151], v[164:167], v[114:117]
	v_mfma_f32_16x16x32_bf16 v[94:97], v[136:139], v[172:175], v[94:97]
	v_mfma_f32_16x16x32_bf16 v[90:93], v[148:151], v[172:175], v[90:93]
	v_mfma_f32_16x16x32_bf16 v[86:89], v[136:139], v[180:183], v[86:89]
	v_mfma_f32_16x16x32_bf16 v[82:85], v[148:151], v[180:183], v[82:85]
	v_mfma_f32_16x16x32_bf16 v[126:129], v[140:143], v[160:163], v[126:129]
	v_mfma_f32_16x16x32_bf16 v[122:125], v[152:155], v[160:163], v[122:125]
	v_mfma_f32_16x16x32_bf16 v[118:121], v[140:143], v[168:171], v[118:121]
	v_mfma_f32_16x16x32_bf16 v[114:117], v[152:155], v[168:171], v[114:117]
	v_mfma_f32_16x16x32_bf16 v[94:97], v[140:143], v[176:179], v[94:97]
	v_mfma_f32_16x16x32_bf16 v[90:93], v[152:155], v[176:179], v[90:93]
	v_mfma_f32_16x16x32_bf16 v[86:89], v[140:143], v[184:187], v[86:89]
	v_mfma_f32_16x16x32_bf16 v[82:85], v[152:155], v[184:187], v[82:85]
	s_setprio 0
	s_barrier
	s_add_i32 s61, 0, 0x14000
	s_add_i32 s0, s11, s50
	v_add_u32_e32 v210, s61, v145
	v_lshl_add_u64 v[214:215], s[44:45], 0, v[0:1]
	s_mov_b32 m0, s0
	ds_read_b128 v[188:191], v210
	ds_read_b128 v[192:195], v210 offset:1024
	ds_read_b128 v[196:199], v210 offset:2048
	ds_read_b128 v[210:213], v210 offset:3072
	global_load_lds_dwordx4 v[214:215], off
	v_lshl_add_u64 v[216:217], s[44:45], 0, v[130:131]
	s_add_i32 m0, s0, 0x2000
	s_nop 0
	global_load_lds_dwordx4 v[216:217], off
	s_barrier
	s_waitcnt lgkmcnt(0)
	s_setprio 1
	s_waitcnt lgkmcnt(0)
	v_mfma_f32_16x16x32_bf16 v[110:113], v[188:191], v[156:159], v[110:113]
	v_mfma_f32_16x16x32_bf16 v[106:109], v[196:199], v[156:159], v[106:109]
	v_mfma_f32_16x16x32_bf16 v[102:105], v[188:191], v[164:167], v[102:105]
	v_mfma_f32_16x16x32_bf16 v[98:101], v[196:199], v[164:167], v[98:101]
	v_mfma_f32_16x16x32_bf16 v[78:81], v[188:191], v[172:175], v[78:81]
	v_mfma_f32_16x16x32_bf16 v[74:77], v[196:199], v[172:175], v[74:77]
	v_mfma_f32_16x16x32_bf16 v[70:73], v[188:191], v[180:183], v[70:73]
	v_mfma_f32_16x16x32_bf16 v[66:69], v[196:199], v[180:183], v[66:69]
	v_mfma_f32_16x16x32_bf16 v[110:113], v[192:195], v[160:163], v[110:113]
	v_mfma_f32_16x16x32_bf16 v[106:109], v[210:213], v[160:163], v[106:109]
	v_mfma_f32_16x16x32_bf16 v[102:105], v[192:195], v[168:171], v[102:105]
	v_mfma_f32_16x16x32_bf16 v[98:101], v[210:213], v[168:171], v[98:101]
	v_mfma_f32_16x16x32_bf16 v[78:81], v[192:195], v[176:179], v[78:81]
	v_mfma_f32_16x16x32_bf16 v[74:77], v[210:213], v[176:179], v[74:77]
	v_mfma_f32_16x16x32_bf16 v[70:73], v[192:195], v[184:187], v[70:73]
	v_mfma_f32_16x16x32_bf16 v[66:69], v[210:213], v[184:187], v[66:69]
	s_setprio 0
	s_mov_b32 m0, s51
	v_lshl_add_u64 v[218:219], s[46:47], 0, v[0:1]
	s_barrier
	ds_read_b128 v[156:159], v147 offset:16384
	ds_read_b128 v[160:163], v147 offset:17408
	ds_read_b128 v[164:167], v147 offset:18432
	ds_read_b128 v[168:171], v147 offset:19456
	ds_read_b128 v[172:175], v147 offset:20480
	ds_read_b128 v[176:179], v147 offset:21504
	ds_read_b128 v[180:183], v147 offset:22528
	ds_read_b128 v[184:187], v147 offset:23552
	global_load_lds_dwordx4 v[218:219], off
	v_lshl_add_u64 v[220:221], s[46:47], 0, v[130:131]
	s_mov_b32 m0, s52
	s_nop 0
	global_load_lds_dwordx4 v[220:221], off
	s_waitcnt vmcnt(10)
	s_barrier
	s_waitcnt lgkmcnt(0)
	s_setprio 1
	s_waitcnt lgkmcnt(0)
	v_mfma_f32_16x16x32_bf16 v[62:65], v[136:139], v[156:159], v[62:65]
	v_mfma_f32_16x16x32_bf16 v[58:61], v[148:151], v[156:159], v[58:61]
	v_mfma_f32_16x16x32_bf16 v[54:57], v[136:139], v[164:167], v[54:57]
	v_mfma_f32_16x16x32_bf16 v[50:53], v[148:151], v[164:167], v[50:53]
	v_mfma_f32_16x16x32_bf16 v[30:33], v[136:139], v[172:175], v[30:33]
	v_mfma_f32_16x16x32_bf16 v[26:29], v[148:151], v[172:175], v[26:29]
	v_mfma_f32_16x16x32_bf16 v[22:25], v[136:139], v[180:183], v[22:25]
	v_mfma_f32_16x16x32_bf16 v[18:21], v[148:151], v[180:183], v[18:21]
	v_mfma_f32_16x16x32_bf16 v[62:65], v[140:143], v[160:163], v[62:65]
	v_mfma_f32_16x16x32_bf16 v[58:61], v[152:155], v[160:163], v[58:61]
	v_mfma_f32_16x16x32_bf16 v[54:57], v[140:143], v[168:171], v[54:57]
	v_mfma_f32_16x16x32_bf16 v[50:53], v[152:155], v[168:171], v[50:53]
	v_mfma_f32_16x16x32_bf16 v[30:33], v[140:143], v[176:179], v[30:33]
	v_mfma_f32_16x16x32_bf16 v[26:29], v[152:155], v[176:179], v[26:29]
	v_mfma_f32_16x16x32_bf16 v[22:25], v[140:143], v[184:187], v[22:25]
	v_mfma_f32_16x16x32_bf16 v[18:21], v[152:155], v[184:187], v[18:21]
	s_setprio 0
	s_barrier
; #define PG8_STAGE(bufoff, gbase, voff) do { _Pragma("unroll") for (int _i = 0; _i < 2; ++_i) \
;         __builtin_amdgcn_global_load_lds((const unsigned*)((const char*)(gbase) + (voff)[_i]), (LAS unsigned*)(lds + (bufoff) + ldsw + _i * 8192), 16, 0, 0); } while (0)
; #define PG8_LDA(dst, b, h) do { _Pragma("unroll") for (int m = 0; m < 4; ++m) _Pragma("unroll") for (int k = 0; k < 2; ++k) dst[m][k] = *(const LAS bf16x8*)(lds + PG8_SA(b, h) + aoff + m * 2048 + k * 1024); } while (0)
; #define PG8_LDB(dst, b, h) do { _Pragma("unroll") for (int n = 0; n < 2; ++n) _Pragma("unroll") for (int k = 0; k < 2; ++k) dst[n][k] = *(const LAS bf16x8*)(lds + PG8_SB(b, h) + boff + n * 2048 + k * 1024); } while (0)
; #define PG8_MMA(ai, bj, At, Bt) do { __builtin_amdgcn_s_setprio(1); _Pragma("unroll") for (int m = 0; m < 4; ++m) _Pragma("unroll") for (int n = 0; n < 2; ++n) _Pragma("unroll") for (int k = 0; k < 2; ++k) \
;         acc[ai][bj][m][n] = __builtin_amdgcn_mfma_f32_16x16x32_bf16(Bt[n][k], At[m][k], acc[ai][bj][m][n], 0, 0, 0); __builtin_amdgcn_s_setprio(0); } while (0)
; #define PG8_WAIT_V(n) asm volatile("s_waitcnt vmcnt(" #n ")" ::: "memory")
; #define PG8_WAIT_L(n) asm volatile("s_waitcnt lgkmcnt(" #n ")" ::: "memory")
; #define PG8_BAR __builtin_amdgcn_s_barrier()
; #define PG8_SCHED __builtin_amdgcn_sched_barrier(0)
; #define PG8_WAIT_V(n) asm volatile("s_waitcnt vmcnt(" #n ")" ::: "memory")
; #define PG8_WAIT_L(n) asm volatile("s_waitcnt lgkmcnt(" #n ")" ::: "memory")
; template <class Epi, class Sched>
; DI void gemm_phase(LAS unsigned char* lds, const Gemm g, const Sched& S, const Epi& E) {
;     ...
;             PG8_STAGE(PG8_SB(0, 1), b2 + hstepB, voffB);
;             PG8_WAIT_V(6); PG8_BAR; PG8_MMA(1, 1, At, B1); PG8_BAR;
;             PG8_LDB(B0, 1, 0); PG8_SCHED; PG8_LDA(At, 1, 0); PG8_STAGE(PG8_SA(0, 1), a2 + hstepA, voffA);
;             PG8_WAIT_L(8); PG8_BAR; PG8_WAIT_L(0); PG8_MMA(0, 0, At, B0); PG8_BAR; PG8_SCHED;
;             PG8_LDB(B1, 1, 1); PG8_STAGE(PG8_SB(1, 0), b3, voffB);
;             PG8_BAR; PG8_WAIT_L(0); PG8_MMA(0, 1, At, B1); PG8_BAR;
;             PG8_LDA(At, 1, 1); PG8_STAGE(PG8_SA(1, 0), a3, voffA);
;             PG8_BAR; PG8_WAIT_L(0); PG8_MMA(1, 0, At, B0); PG8_BAR; PG8_SCHED;
;             PG8_STAGE(PG8_SB(1, 1), b3 + hstepB, voffB);
;             PG8_WAIT_V(6); PG8_BAR; PG8_MMA(1, 1, At, B1); PG8_BAR;
	s_add_u32 s0, s44, 0x40000
	s_addc_u32 s1, s45, 0
	s_add_i32 s11, s61, s50
	v_lshl_add_u64 v[136:137], s[0:1], 0, v[0:1]
	s_mov_b32 m0, s11
	s_nop 0
	global_load_lds_dwordx4 v[136:137], off
	v_lshl_add_u64 v[136:137], s[0:1], 0, v[130:131]
	s_add_i32 m0, s11, 0x2000
	s_nop 0
	global_load_lds_dwordx4 v[136:137], off
	v_add_u32_e32 v152, 0x18000, v145
	ds_read_b128 v[136:139], v152
	ds_read_b128 v[140:143], v152 offset:1024
	ds_read_b128 v[148:151], v152 offset:2048
	ds_read_b128 v[152:155], v152 offset:3072
	s_waitcnt vmcnt(6)
	s_barrier
	s_setprio 1
	v_mfma_f32_16x16x32_bf16 v[46:49], v[188:191], v[156:159], v[46:49]
	v_mfma_f32_16x16x32_bf16 v[42:45], v[196:199], v[156:159], v[42:45]
	v_mfma_f32_16x16x32_bf16 v[38:41], v[188:191], v[164:167], v[38:41]
	v_mfma_f32_16x16x32_bf16 v[34:37], v[196:199], v[164:167], v[34:37]
	v_mfma_f32_16x16x32_bf16 v[14:17], v[188:191], v[172:175], v[14:17]
	v_mfma_f32_16x16x32_bf16 v[10:13], v[196:199], v[172:175], v[10:13]
	v_mfma_f32_16x16x32_bf16 v[6:9], v[188:191], v[180:183], v[6:9]
	v_mfma_f32_16x16x32_bf16 v[2:5], v[196:199], v[180:183], v[2:5]
	v_mfma_f32_16x16x32_bf16 v[46:49], v[192:195], v[160:163], v[46:49]
	v_mfma_f32_16x16x32_bf16 v[42:45], v[210:213], v[160:163], v[42:45]
	v_mfma_f32_16x16x32_bf16 v[38:41], v[192:195], v[168:171], v[38:41]
	v_mfma_f32_16x16x32_bf16 v[34:37], v[210:213], v[168:171], v[34:37]
	v_mfma_f32_16x16x32_bf16 v[14:17], v[192:195], v[176:179], v[14:17]
	v_mfma_f32_16x16x32_bf16 v[10:13], v[210:213], v[176:179], v[10:13]
	v_mfma_f32_16x16x32_bf16 v[6:9], v[192:195], v[184:187], v[6:9]
	v_mfma_f32_16x16x32_bf16 v[2:5], v[210:213], v[184:187], v[2:5]
	s_setprio 0
	s_add_i32 s11, 0, 0x18000
	s_barrier
	s_add_u32 s0, s46, 0x40000
	s_addc_u32 s1, s47, 0
	s_mov_b32 m0, s53
	v_lshl_add_u64 v[188:189], s[0:1], 0, v[0:1]
	ds_read_b128 v[156:159], v147 offset:32768
	ds_read_b128 v[160:163], v147 offset:33792
	ds_read_b128 v[164:167], v147 offset:34816
	ds_read_b128 v[168:171], v147 offset:35840
	ds_read_b128 v[172:175], v147 offset:36864
	ds_read_b128 v[176:179], v147 offset:37888
	ds_read_b128 v[180:183], v147 offset:38912
	ds_read_b128 v[184:187], v147 offset:39936
	global_load_lds_dwordx4 v[188:189], off
	v_lshl_add_u64 v[188:189], s[0:1], 0, v[130:131]
	s_mov_b32 m0, s54
	s_nop 0
	global_load_lds_dwordx4 v[188:189], off
	s_waitcnt lgkmcnt(8)
	s_barrier
	s_waitcnt lgkmcnt(0)
	s_setprio 1
	s_waitcnt lgkmcnt(0)
	v_mfma_f32_16x16x32_bf16 v[126:129], v[136:139], v[156:159], v[126:129]
	v_mfma_f32_16x16x32_bf16 v[122:125], v[148:151], v[156:159], v[122:125]
	v_mfma_f32_16x16x32_bf16 v[118:121], v[136:139], v[164:167], v[118:121]
	v_mfma_f32_16x16x32_bf16 v[114:117], v[148:151], v[164:167], v[114:117]
	v_mfma_f32_16x16x32_bf16 v[94:97], v[136:139], v[172:175], v[94:97]
	v_mfma_f32_16x16x32_bf16 v[90:93], v[148:151], v[172:175], v[90:93]
	v_mfma_f32_16x16x32_bf16 v[86:89], v[136:139], v[180:183], v[86:89]
	v_mfma_f32_16x16x32_bf16 v[82:85], v[148:151], v[180:183], v[82:85]
	v_mfma_f32_16x16x32_bf16 v[126:129], v[140:143], v[160:163], v[126:129]
	v_mfma_f32_16x16x32_bf16 v[122:125], v[152:155], v[160:163], v[122:125]
	v_mfma_f32_16x16x32_bf16 v[118:121], v[140:143], v[168:171], v[118:121]
	v_mfma_f32_16x16x32_bf16 v[114:117], v[152:155], v[168:171], v[114:117]
	v_mfma_f32_16x16x32_bf16 v[94:97], v[140:143], v[176:179], v[94:97]
	v_mfma_f32_16x16x32_bf16 v[90:93], v[152:155], v[176:179], v[90:93]
	v_mfma_f32_16x16x32_bf16 v[86:89], v[140:143], v[184:187], v[86:89]
	v_mfma_f32_16x16x32_bf16 v[82:85], v[152:155], v[184:187], v[82:85]
	s_setprio 0
	s_barrier
	s_add_i32 s46, 0, 0x1c000
	s_add_i32 s0, s11, s50
	v_add_u32_e32 v210, s46, v145
	v_lshl_add_u64 v[214:215], v[214:215], 0, s[16:17]
	s_mov_b32 m0, s0
	ds_read_b128 v[188:191], v210
	ds_read_b128 v[192:195], v210 offset:1024
	ds_read_b128 v[196:199], v210 offset:2048
	ds_read_b128 v[210:213], v210 offset:3072
	global_load_lds_dwordx4 v[214:215], off
	v_lshl_add_u64 v[214:215], v[216:217], 0, s[16:17]
	s_add_i32 m0, s0, 0x2000
	s_nop 0
	global_load_lds_dwordx4 v[214:215], off
	s_barrier
	s_waitcnt lgkmcnt(0)
	s_setprio 1
	s_waitcnt lgkmcnt(0)
	v_mfma_f32_16x16x32_bf16 v[110:113], v[188:191], v[156:159], v[110:113]
	v_mfma_f32_16x16x32_bf16 v[106:109], v[196:199], v[156:159], v[106:109]
	v_mfma_f32_16x16x32_bf16 v[102:105], v[188:191], v[164:167], v[102:105]
	v_mfma_f32_16x16x32_bf16 v[98:101], v[196:199], v[164:167], v[98:101]
	v_mfma_f32_16x16x32_bf16 v[78:81], v[188:191], v[172:175], v[78:81]
	v_mfma_f32_16x16x32_bf16 v[74:77], v[196:199], v[172:175], v[74:77]
	v_mfma_f32_16x16x32_bf16 v[70:73], v[188:191], v[180:183], v[70:73]
	v_mfma_f32_16x16x32_bf16 v[66:69], v[196:199], v[180:183], v[66:69]
	v_mfma_f32_16x16x32_bf16 v[110:113], v[192:195], v[160:163], v[110:113]
	v_mfma_f32_16x16x32_bf16 v[106:109], v[210:213], v[160:163], v[106:109]
	v_mfma_f32_16x16x32_bf16 v[102:105], v[192:195], v[168:171], v[102:105]
	v_mfma_f32_16x16x32_bf16 v[98:101], v[210:213], v[168:171], v[98:101]
	v_mfma_f32_16x16x32_bf16 v[78:81], v[192:195], v[176:179], v[78:81]
	v_mfma_f32_16x16x32_bf16 v[74:77], v[210:213], v[176:179], v[74:77]
	v_mfma_f32_16x16x32_bf16 v[70:73], v[192:195], v[184:187], v[70:73]
	v_mfma_f32_16x16x32_bf16 v[66:69], v[210:213], v[184:187], v[66:69]
	s_setprio 0
	s_mov_b32 m0, s55
	v_lshl_add_u64 v[214:215], v[218:219], 0, s[16:17]
	s_barrier
	ds_read_b128 v[156:159], v147 offset:49152
	ds_read_b128 v[160:163], v147 offset:50176
	ds_read_b128 v[164:167], v147 offset:51200
	ds_read_b128 v[168:171], v147 offset:52224
	ds_read_b128 v[172:175], v147 offset:53248
	ds_read_b128 v[176:179], v147 offset:54272
	ds_read_b128 v[180:183], v147 offset:55296
	ds_read_b128 v[184:187], v147 offset:56320
	global_load_lds_dwordx4 v[214:215], off
	v_lshl_add_u64 v[214:215], v[220:221], 0, s[16:17]
	s_mov_b32 m0, s56
	s_nop 0
	global_load_lds_dwordx4 v[214:215], off
	s_waitcnt vmcnt(10)
	s_barrier
; #define PG8_STAGE(bufoff, gbase, voff) do { _Pragma("unroll") for (int _i = 0; _i < 2; ++_i) \
;         __builtin_amdgcn_global_load_lds((const unsigned*)((const char*)(gbase) + (voff)[_i]), (LAS unsigned*)(lds + (bufoff) + ldsw + _i * 8192), 16, 0, 0); } while (0)
; #define PG8_MMA(ai, bj, At, Bt) do { __builtin_amdgcn_s_setprio(1); _Pragma("unroll") for (int m = 0; m < 4; ++m) _Pragma("unroll") for (int n = 0; n < 2; ++n) _Pragma("unroll") for (int k = 0; k < 2; ++k) \
;         acc[ai][bj][m][n] = __builtin_amdgcn_mfma_f32_16x16x32_bf16(Bt[n][k], At[m][k], acc[ai][bj][m][n], 0, 0, 0); __builtin_amdgcn_s_setprio(0); } while (0)
; #define PG8_WAIT_V(n) asm volatile("s_waitcnt vmcnt(" #n ")" ::: "memory")
; #define PG8_WAIT_L(n) asm volatile("s_waitcnt lgkmcnt(" #n ")" ::: "memory")
; #define PG8_BAR __builtin_amdgcn_s_barrier()
; #define PG8_SCHED __builtin_amdgcn_sched_barrier(0)
; #define PG8_BAR __builtin_amdgcn_s_barrier()
; template <class Epi, class Sched>
; DI void gemm_phase(LAS unsigned char* lds, const Gemm g, const Sched& S, const Epi& E) {
;     ...
;             PG8_BAR; PG8_WAIT_L(0); PG8_MMA(1, 0, At, B0); PG8_BAR; PG8_SCHED;
;             PG8_STAGE(PG8_SB(1, 1), b3 + hstepB, voffB);
;             PG8_WAIT_V(6); PG8_BAR; PG8_MMA(1, 1, At, B1); PG8_BAR;
;         }
;         if constexpr (!Epi::AFTER_DRAIN) { E(acc, cur, wr, wc, fr, fq); S.done(cur); }
;   DI void operator()(const f32x4 (&acc)[2][2][4][2], const Unit& u, int wr, int wc, int fr, int fq) const {
;     const int row0 = u.pm * BM + wr * 64 + fr, col0 = u.pn * BM + wc * 32 + 4 * fq;
; #pragma unroll
;     for (int ai = 0; ai < 2; ++ai)
; #pragma unroll
;       for (int mp = 0; mp < 2; ++mp) {
;         f32x4 xv[2][2][2];
; #pragma unroll
;         for (int mm = 0; mm < 2; ++mm)
; #pragma unroll
;           for (int bj = 0; bj < 2; ++bj)
; #pragma unroll
;             for (int n = 0; n < 2; ++n)
;               xv[mm][bj][n] = *(const f32x4*)(X + (size_t)(row0 + ai * HALF + (mp * 2 + mm) * 16) * 1024 + col0 + bj * HALF + n * 16);
; #pragma unroll
;         for (int mm = 0; mm < 2; ++mm)
; #pragma unroll
;           for (int bj = 0; bj < 2; ++bj)
; #pragma unroll
;             for (int n = 0; n < 2; ++n)
;               *(f32x4*)(O + (size_t)(row0 + ai * HALF + (mp * 2 + mm) * 16) * 1024 + col0 + bj * HALF + n * 16) = xv[mm][bj][n] + acc[ai][bj][mp * 2 + mm][n];
;       }
;   }
	s_waitcnt lgkmcnt(0)
	s_setprio 1
	s_waitcnt lgkmcnt(0)
	v_mfma_f32_16x16x32_bf16 v[62:65], v[136:139], v[156:159], v[62:65]
	v_mfma_f32_16x16x32_bf16 v[58:61], v[148:151], v[156:159], v[58:61]
	v_mfma_f32_16x16x32_bf16 v[54:57], v[136:139], v[164:167], v[54:57]
	v_mfma_f32_16x16x32_bf16 v[50:53], v[148:151], v[164:167], v[50:53]
	v_mfma_f32_16x16x32_bf16 v[30:33], v[136:139], v[172:175], v[30:33]
	v_mfma_f32_16x16x32_bf16 v[26:29], v[148:151], v[172:175], v[26:29]
	v_mfma_f32_16x16x32_bf16 v[22:25], v[136:139], v[180:183], v[22:25]
	v_mfma_f32_16x16x32_bf16 v[18:21], v[148:151], v[180:183], v[18:21]
	v_mfma_f32_16x16x32_bf16 v[62:65], v[140:143], v[160:163], v[62:65]
	v_mfma_f32_16x16x32_bf16 v[58:61], v[152:155], v[160:163], v[58:61]
	v_mfma_f32_16x16x32_bf16 v[54:57], v[140:143], v[168:171], v[54:57]
	v_mfma_f32_16x16x32_bf16 v[50:53], v[152:155], v[168:171], v[50:53]
	v_mfma_f32_16x16x32_bf16 v[30:33], v[140:143], v[176:179], v[30:33]
	v_mfma_f32_16x16x32_bf16 v[26:29], v[152:155], v[176:179], v[26:29]
	v_mfma_f32_16x16x32_bf16 v[22:25], v[140:143], v[184:187], v[22:25]
	v_mfma_f32_16x16x32_bf16 v[18:21], v[152:155], v[184:187], v[18:21]
	s_setprio 0
	s_barrier
	s_add_u32 s0, s44, 0x40080
	s_addc_u32 s1, s45, 0
	s_add_i32 s11, s46, s50
	v_lshl_add_u64 v[136:137], s[0:1], 0, v[0:1]
	s_mov_b32 m0, s11
	s_nop 0
	global_load_lds_dwordx4 v[136:137], off
	v_lshl_add_u64 v[136:137], s[0:1], 0, v[130:131]
	s_add_i32 m0, s11, 0x2000
	s_nop 0
	global_load_lds_dwordx4 v[136:137], off
	v_add_u32_e32 v152, 0x10000, v145
	ds_read_b128 v[136:139], v152
	ds_read_b128 v[140:143], v152 offset:1024
	ds_read_b128 v[148:151], v152 offset:2048
	ds_read_b128 v[152:155], v152 offset:3072
	s_waitcnt vmcnt(6)
	s_barrier
	s_setprio 1
	v_mfma_f32_16x16x32_bf16 v[46:49], v[188:191], v[156:159], v[46:49]
	v_mfma_f32_16x16x32_bf16 v[42:45], v[196:199], v[156:159], v[42:45]
	v_mfma_f32_16x16x32_bf16 v[38:41], v[188:191], v[164:167], v[38:41]
	v_mfma_f32_16x16x32_bf16 v[34:37], v[196:199], v[164:167], v[34:37]
	v_mfma_f32_16x16x32_bf16 v[14:17], v[188:191], v[172:175], v[14:17]
	v_mfma_f32_16x16x32_bf16 v[10:13], v[196:199], v[172:175], v[10:13]
	v_mfma_f32_16x16x32_bf16 v[6:9], v[188:191], v[180:183], v[6:9]
	v_mfma_f32_16x16x32_bf16 v[2:5], v[196:199], v[180:183], v[2:5]
	v_mfma_f32_16x16x32_bf16 v[46:49], v[192:195], v[160:163], v[46:49]
	v_mfma_f32_16x16x32_bf16 v[42:45], v[210:213], v[160:163], v[42:45]
	v_mfma_f32_16x16x32_bf16 v[38:41], v[192:195], v[168:171], v[38:41]
	v_mfma_f32_16x16x32_bf16 v[34:37], v[210:213], v[168:171], v[34:37]
	v_mfma_f32_16x16x32_bf16 v[14:17], v[192:195], v[176:179], v[14:17]
	v_mfma_f32_16x16x32_bf16 v[10:13], v[210:213], v[176:179], v[10:13]
	v_mfma_f32_16x16x32_bf16 v[6:9], v[192:195], v[184:187], v[6:9]
	v_mfma_f32_16x16x32_bf16 v[2:5], v[210:213], v[184:187], v[2:5]
	s_setprio 0
	s_add_i32 s60, s60, 2
	s_add_u32 s58, s58, 0x100
	s_addc_u32 s59, s59, 0
	s_add_u32 s42, s42, 0x100
	s_addc_u32 s43, s43, 0
	s_cmp_gt_u32 s60, 13
	s_barrier
	s_cbranch_scc0 .LBB0_1039
	s_waitcnt lgkmcnt(0)
	s_mov_b32 s92, 0
	s_cmp_eq_u64 s[2:3], s[4:5]
	s_cbranch_scc1 .Lfz_p1
	v_lshl_or_b32 v136, s41, 8, v146
	v_lshl_add_u32 v142, s40, 8, v144
	v_ashrrev_i32_e32 v137, 31, v136
	v_lshlrev_b64 v[136:137], 2, v[136:137]
	v_ashrrev_i32_e32 v143, 31, v142
	v_or_b32_e32 v164, 16, v142
	v_lshl_add_u64 v[138:139], s[2:3], 0, v[136:137]
	v_lshlrev_b64 v[140:141], 12, v[142:143]
	v_ashrrev_i32_e32 v165, 31, v164
	v_lshl_add_u64 v[160:161], v[138:139], 0, v[140:141]
	v_lshlrev_b64 v[180:181], 12, v[164:165]
	global_load_dwordx4 v[148:151], v[160:161], off
	global_load_dwordx4 v[152:155], v[160:161], off offset:64
	global_load_dwordx4 v[156:159], v[160:161], off offset:512
	s_nop 0
	global_load_dwordx4 v[160:163], v[160:161], off offset:576
	v_lshl_add_u64 v[176:177], v[138:139], 0, v[180:181]
	global_load_dwordx4 v[164:167], v[176:177], off
	global_load_dwordx4 v[168:171], v[176:177], off offset:64
	global_load_dwordx4 v[172:175], v[176:177], off offset:512
	s_nop 0
	global_load_dwordx4 v[176:179], v[176:177], off offset:576
	s_mov_b64 s[40:41], 0x80000
	s_mov_b64 s[0:1], 0x90000
	s_and_b64 vcc, exec, s[36:37]
	s_mov_b64 s[42:43], s[38:39]
	s_mov_b64 s[44:45], s[34:35]
	s_waitcnt vmcnt(0)
	v_pk_add_f32 v[126:127], v[126:127], v[148:149]
	v_lshl_add_u64 v[148:149], s[4:5], 0, v[140:141]
	v_lshl_add_u64 v[148:149], v[148:149], 0, v[136:137]
	v_pk_add_f32 v[112:113], v[112:113], v[158:159]
	v_pk_add_f32 v[110:111], v[110:111], v[156:157]
	global_store_dwordx4 v[148:149], v[110:113], off offset:512
	v_pk_add_f32 v[100:101], v[100:101], v[178:179]
	v_pk_add_f32 v[98:99], v[98:99], v[176:177]
	v_lshl_add_u64 v[110:111], s[4:5], 0, v[180:181]
	v_lshl_add_u64 v[110:111], v[110:111], 0, v[136:137]
	v_pk_add_f32 v[108:109], v[108:109], v[162:163]
	v_pk_add_f32 v[106:107], v[106:107], v[160:161]
	global_store_dwordx4 v[110:111], v[98:101], off offset:576
	v_pk_add_f32 v[128:129], v[128:129], v[150:151]
	v_pk_add_f32 v[124:125], v[124:125], v[154:155]
	v_or_b32_e32 v98, 32, v142
	v_pk_add_f32 v[122:123], v[122:123], v[152:153]
	global_store_dwordx4 v[148:149], v[106:109], off offset:576
	v_ashrrev_i32_e32 v99, 31, v98
	global_store_dwordx4 v[148:149], v[126:129], off
	v_pk_add_f32 v[108:109], v[120:121], v[166:167]
	v_pk_add_f32 v[106:107], v[118:119], v[164:165]
	global_store_dwordx4 v[148:149], v[122:125], off offset:64
	global_store_dwordx4 v[110:111], v[106:109], off
	v_pk_add_f32 v[104:105], v[104:105], v[174:175]
	v_pk_add_f32 v[102:103], v[102:103], v[172:173]
	v_pk_add_f32 v[108:109], v[116:117], v[170:171]
	v_pk_add_f32 v[106:107], v[114:115], v[168:169]
	v_lshlrev_b64 v[148:149], 12, v[98:99]
	v_or_b32_e32 v114, 48, v142
	global_store_dwordx4 v[110:111], v[106:109], off offset:64
	global_store_dwordx4 v[110:111], v[102:105], off offset:512
	v_lshl_add_u64 v[110:111], v[138:139], 0, v[148:149]
	v_ashrrev_i32_e32 v115, 31, v114
	global_load_dwordx4 v[98:101], v[110:111], off
	global_load_dwordx4 v[102:105], v[110:111], off offset:64
	global_load_dwordx4 v[106:109], v[110:111], off offset:512
	s_nop 0
	global_load_dwordx4 v[110:113], v[110:111], off offset:576
	v_lshlrev_b64 v[142:143], 12, v[114:115]
	v_lshl_add_u64 v[126:127], v[138:139], 0, v[142:143]
	global_load_dwordx4 v[114:117], v[126:127], off
	global_load_dwordx4 v[118:121], v[126:127], off offset:64
	global_load_dwordx4 v[122:125], v[126:127], off offset:512
	s_nop 0
	global_load_dwordx4 v[126:129], v[126:127], off offset:576
	s_waitcnt vmcnt(0)
; #define PG8_WAIT_V(n) asm volatile("s_waitcnt vmcnt(" #n ")" ::: "memory")
; #define PG8_BAR __builtin_amdgcn_s_barrier()
; #define PG8_WAIT_V(n) asm volatile("s_waitcnt vmcnt(" #n ")" ::: "memory")
; #define PG8_BAR __builtin_amdgcn_s_barrier()
; template <class Epi, class Sched>
; DI void gemm_phase(LAS unsigned char* lds, const Gemm g, const Sched& S, const Epi& E) {
;     ...
;         if constexpr (!Epi::AFTER_DRAIN) { E(acc, cur, wr, wc, fr, fq); S.done(cur); }
;         if (!has_next) break;
; #pragma unroll
;         for (int a = 0; a < 2; ++a)
; #pragma unroll
;             for (int b = 0; b < 2; ++b)
; #pragma unroll
;                 for (int m = 0; m < 4; ++m)
; #pragma unroll
;                     for (int n = 0; n < 2; ++n) acc[a][b][m][n] = (f32x4){0.f, 0.f, 0.f, 0.f};
;         cur = nxt; cA = nA; cB = nB; ++ui;
;     }
;     PG8_WAIT_V(0);
;     if (wr == 0) PG8_BAR;
;     PG8_BAR;
;   DI void operator()(const f32x4 (&acc)[2][2][4][2], const Unit& u, int wr, int wc, int fr, int fq) const {
;     ...
; #pragma unroll
;     for (int ai = 0; ai < 2; ++ai)
; #pragma unroll
;       for (int mp = 0; mp < 2; ++mp) {
;         f32x4 xv[2][2][2];
; #pragma unroll
;         for (int mm = 0; mm < 2; ++mm)
; #pragma unroll
;           for (int bj = 0; bj < 2; ++bj)
; #pragma unroll
;             for (int n = 0; n < 2; ++n)
;               xv[mm][bj][n] = *(const f32x4*)(X + (size_t)(row0 + ai * HALF + (mp * 2 + mm) * 16) * 1024 + col0 + bj * HALF + n * 16);
; #pragma unroll
;         for (int mm = 0; mm < 2; ++mm)
; #pragma unroll
;           for (int bj = 0; bj < 2; ++bj)
; #pragma unroll
;             for (int n = 0; n < 2; ++n)
;               *(f32x4*)(O + (size_t)(row0 + ai * HALF + (mp * 2 + mm) * 16) * 1024 + col0 + bj * HALF + n * 16) = xv[mm][bj][n] + acc[ai][bj][mp * 2 + mm][n];
;       }
;   }
	v_pk_add_f32 v[94:95], v[94:95], v[98:99]
	v_lshl_add_u64 v[98:99], s[4:5], 0, v[148:149]
	v_lshl_add_u64 v[98:99], v[98:99], 0, v[136:137]
	v_pk_add_f32 v[80:81], v[80:81], v[108:109]
	v_pk_add_f32 v[78:79], v[78:79], v[106:107]
	global_store_dwordx4 v[98:99], v[78:81], off offset:512
	v_pk_add_f32 v[76:77], v[76:77], v[112:113]
	v_pk_add_f32 v[74:75], v[74:75], v[110:111]
	v_lshl_add_u64 v[78:79], s[4:5], 0, v[142:143]
	v_pk_add_f32 v[96:97], v[96:97], v[100:101]
	v_pk_add_f32 v[92:93], v[92:93], v[104:105]
	v_pk_add_f32 v[90:91], v[90:91], v[102:103]
	global_store_dwordx4 v[98:99], v[74:77], off offset:576
	v_lshl_add_u64 v[78:79], v[78:79], 0, v[136:137]
	global_store_dwordx4 v[98:99], v[94:97], off
	v_pk_add_f32 v[76:77], v[88:89], v[116:117]
	v_pk_add_f32 v[74:75], v[86:87], v[114:115]
	global_store_dwordx4 v[98:99], v[90:93], off offset:64
	global_store_dwordx4 v[78:79], v[74:77], off
	v_pk_add_f32 v[72:73], v[72:73], v[124:125]
	v_pk_add_f32 v[70:71], v[70:71], v[122:123]
	v_pk_add_f32 v[76:77], v[84:85], v[120:121]
	v_pk_add_f32 v[74:75], v[82:83], v[118:119]
	v_pk_add_f32 v[68:69], v[68:69], v[128:129]
	v_pk_add_f32 v[66:67], v[66:67], v[126:127]
	v_lshl_add_u64 v[98:99], v[140:141], 0, s[40:41]
	global_store_dwordx4 v[78:79], v[74:77], off offset:64
	global_store_dwordx4 v[78:79], v[70:73], off offset:512
	global_store_dwordx4 v[78:79], v[66:69], off offset:576
	v_lshl_add_u64 v[78:79], v[138:139], 0, v[98:99]
	global_load_dwordx4 v[66:69], v[78:79], off
	global_load_dwordx4 v[70:73], v[78:79], off offset:64
	global_load_dwordx4 v[74:77], v[78:79], off offset:512
	s_nop 0
	global_load_dwordx4 v[78:81], v[78:79], off offset:576
	v_lshl_add_u64 v[100:101], v[140:141], 0, s[0:1]
	v_lshl_add_u64 v[94:95], v[138:139], 0, v[100:101]
	global_load_dwordx4 v[82:85], v[94:95], off
	global_load_dwordx4 v[86:89], v[94:95], off offset:64
	global_load_dwordx4 v[90:93], v[94:95], off offset:512
	s_nop 0
	global_load_dwordx4 v[94:97], v[94:95], off offset:576
	s_mov_b64 s[40:41], 0xa0000
	s_mov_b64 s[0:1], 0xb0000
	s_waitcnt vmcnt(0)
	v_pk_add_f32 v[62:63], v[62:63], v[66:67]
	v_lshl_add_u64 v[66:67], s[4:5], 0, v[98:99]
	v_lshl_add_u64 v[66:67], v[66:67], 0, v[136:137]
	v_pk_add_f32 v[48:49], v[48:49], v[76:77]
	v_pk_add_f32 v[46:47], v[46:47], v[74:75]
	global_store_dwordx4 v[66:67], v[46:49], off offset:512
	v_pk_add_f32 v[44:45], v[44:45], v[80:81]
	v_pk_add_f32 v[42:43], v[42:43], v[78:79]
	v_lshl_add_u64 v[46:47], s[4:5], 0, v[100:101]
	v_pk_add_f32 v[64:65], v[64:65], v[68:69]
	v_pk_add_f32 v[60:61], v[60:61], v[72:73]
	v_pk_add_f32 v[58:59], v[58:59], v[70:71]
	global_store_dwordx4 v[66:67], v[42:45], off offset:576
	v_lshl_add_u64 v[46:47], v[46:47], 0, v[136:137]
	global_store_dwordx4 v[66:67], v[62:65], off
	v_pk_add_f32 v[44:45], v[56:57], v[84:85]
	v_pk_add_f32 v[42:43], v[54:55], v[82:83]
	global_store_dwordx4 v[66:67], v[58:61], off offset:64
	global_store_dwordx4 v[46:47], v[42:45], off
	v_pk_add_f32 v[40:41], v[40:41], v[92:93]
	v_pk_add_f32 v[38:39], v[38:39], v[90:91]
	v_pk_add_f32 v[44:45], v[52:53], v[88:89]
	v_pk_add_f32 v[42:43], v[50:51], v[86:87]
	v_pk_add_f32 v[36:37], v[36:37], v[96:97]
	v_pk_add_f32 v[34:35], v[34:35], v[94:95]
	v_lshl_add_u64 v[66:67], v[140:141], 0, s[40:41]
	global_store_dwordx4 v[46:47], v[42:45], off offset:64
	global_store_dwordx4 v[46:47], v[38:41], off offset:512
	global_store_dwordx4 v[46:47], v[34:37], off offset:576
	v_lshl_add_u64 v[46:47], v[138:139], 0, v[66:67]
	global_load_dwordx4 v[34:37], v[46:47], off
	global_load_dwordx4 v[38:41], v[46:47], off offset:64
	global_load_dwordx4 v[42:45], v[46:47], off offset:512
	s_nop 0
	global_load_dwordx4 v[46:49], v[46:47], off offset:576
	v_lshl_add_u64 v[68:69], v[140:141], 0, s[0:1]
	v_lshl_add_u64 v[62:63], v[138:139], 0, v[68:69]
	global_load_dwordx4 v[50:53], v[62:63], off
	global_load_dwordx4 v[54:57], v[62:63], off offset:64
	global_load_dwordx4 v[58:61], v[62:63], off offset:512
	s_nop 0
	global_load_dwordx4 v[62:65], v[62:63], off offset:576
	s_mov_b32 s41, s8
	s_mov_b32 s40, s12
	s_waitcnt vmcnt(0)
	v_pk_add_f32 v[30:31], v[30:31], v[34:35]
	v_lshl_add_u64 v[34:35], s[4:5], 0, v[66:67]
	v_lshl_add_u64 v[34:35], v[34:35], 0, v[136:137]
	v_pk_add_f32 v[16:17], v[16:17], v[44:45]
	v_pk_add_f32 v[14:15], v[14:15], v[42:43]
	global_store_dwordx4 v[34:35], v[14:17], off offset:512
	v_pk_add_f32 v[12:13], v[12:13], v[48:49]
	v_pk_add_f32 v[10:11], v[10:11], v[46:47]
	v_lshl_add_u64 v[14:15], s[4:5], 0, v[68:69]
	global_store_dwordx4 v[34:35], v[10:13], off offset:576
	v_lshl_add_u64 v[14:15], v[14:15], 0, v[136:137]
	v_pk_add_f32 v[32:33], v[32:33], v[36:37]
	v_pk_add_f32 v[12:13], v[24:25], v[52:53]
	v_pk_add_f32 v[10:11], v[22:23], v[50:51]
	v_pk_add_f32 v[28:29], v[28:29], v[40:41]
	v_pk_add_f32 v[26:27], v[26:27], v[38:39]
	global_store_dwordx4 v[14:15], v[10:13], off
	v_pk_add_f32 v[8:9], v[8:9], v[60:61]
	v_pk_add_f32 v[6:7], v[6:7], v[58:59]
	v_pk_add_f32 v[12:13], v[20:21], v[56:57]
	v_pk_add_f32 v[10:11], v[18:19], v[54:55]
	v_pk_add_f32 v[4:5], v[4:5], v[64:65]
	v_pk_add_f32 v[2:3], v[2:3], v[62:63]
	global_store_dwordx4 v[34:35], v[30:33], off
	global_store_dwordx4 v[34:35], v[26:29], off offset:64
	global_store_dwordx4 v[14:15], v[10:13], off offset:64
	global_store_dwordx4 v[14:15], v[6:9], off offset:512
	global_store_dwordx4 v[14:15], v[2:5], off offset:576
.Lfz_p1_ret:
	s_cbranch_vccz .LBB0_1032
	s_waitcnt vmcnt(0)
	s_cmpk_gt_u32 s20, 0xff
	s_cbranch_scc1 .LBB0_1043
	s_barrier

; DI int tidx() { int t = threadIdx.x; asm volatile("" : "+v"(t)); return t; }
; DI int bidx() { int b = blockIdx.x; asm volatile("" : "+s"(b)); return b; }
; DI float wave_sum_fast(float v) { v = fdpp_add(v, 0); v = fdpp_add(v, 1); v = fdpp_add(v, 2); v = fdpp_add(v, 3); v = xor16_sum(v); return xor32_sum(v); }
; DI void rmsnorm_rows(const float* x, const float* g, bf16_t* outb, float* outf) {
;   const int lane = tidx() & 63, w = tidx() >> 6;
;   for (int it = bidx(); it < NTOK / 16; it += gridDim.x) {
;     float4 v[2][4]; float ss[2] = {0.f, 0.f};
; #pragma unroll
;     for (int rr = 0; rr < 2; ++rr) {
;       const float* xr = x + (size_t)(it * 16 + rr * 8 + w) * 1024;
; #pragma unroll
;       for (int i = 0; i < 4; ++i) v[rr][i] = *(const float4*)(xr + lane * 4 + 256 * i);
;     }
;     float4 gg[4];
; #pragma unroll
;     for (int i = 0; i < 4; ++i) gg[i] = *(const float4*)(g + lane * 4 + 256 * i);
; #pragma unroll
;     for (int rr = 0; rr < 2; ++rr) {
; #pragma unroll
;       for (int i = 0; i < 4; ++i) ss[rr] += v[rr][i].x * v[rr][i].x + v[rr][i].y * v[rr][i].y + v[rr][i].z * v[rr][i].z + v[rr][i].w * v[rr][i].w;
;       ss[rr] = wave_sum_fast(ss[rr]);
;     }
; #pragma unroll
;     for (int rr = 0; rr < 2; ++rr) {
;       const int row = it * 16 + rr * 8 + w;
.LBB0_1044:
	s_cmp_eq_u32 s92, 1
	s_cbranch_scc0 .Lfz_nox
	v_lshrrev_b32_e32 v191, 6, v201
	v_lshrrev_b32_e32 v192, 2, v191
	v_and_b32_e32 v193, 3, v191
	v_and_b32_e32 v194, 15, v201
	v_bfe_u32 v195, v201, 4, 2
	v_lshl_or_b32 v196, v192, 6, v194
	v_lshl_or_b32 v197, v193, 2, v195
	v_lshlrev_b32_e32 v196, 6, v196
	v_lshl_add_u32 v196, v197, 2, v196
	v_add_u32_e32 v196, 0x20000, v196
	ds_write_b32 v196, v182
	ds_write_b32 v196, v183 offset:1024
	ds_write_b32 v196, v184 offset:2048
	ds_write_b32 v196, v185 offset:3072
	ds_write_b32 v196, v186 offset:8192
	ds_write_b32 v196, v187 offset:9216
	ds_write_b32 v196, v188 offset:10240
	ds_write_b32 v196, v189 offset:11264
	v_readlane_b32 s94, v252, 6
	v_readlane_b32 s95, v252, 7
	s_load_dwordx2 s[94:95], s[94:95], 0xf0
	s_waitcnt lgkmcnt(0)
	s_barrier
	v_cmp_gt_u32_e32 vcc, 0x100, v201
	s_and_saveexec_b64 s[96:97], vcc
	v_lshlrev_b32_e32 v197, 6, v201
	v_add_u32_e32 v197, 0x20000, v197
	ds_read_b128 v[150:153], v197
	ds_read_b128 v[154:157], v197 offset:16
	ds_read_b128 v[158:161], v197 offset:32
	ds_read_b128 v[162:165], v197 offset:48
	s_lshl_b32 s93, s91, 16
	s_lshl_b32 s88, s90, 10
	s_add_u32 s93, s93, s88
	s_add_u32 s94, s94, 0xaaa4500
	s_addc_u32 s95, s95, 0
	s_add_u32 s94, s94, s93
	s_addc_u32 s95, s95, 0
	v_lshlrev_b32_e32 v198, 2, v201
	s_waitcnt lgkmcnt(0)
	v_add_f32_e32 v150, v150, v151
	v_add_f32_e32 v150, v150, v152
	v_add_f32_e32 v150, v150, v153
	v_add_f32_e32 v150, v150, v154
	v_add_f32_e32 v150, v150, v155
	v_add_f32_e32 v150, v150, v156
	v_add_f32_e32 v150, v150, v157
	v_add_f32_e32 v150, v150, v158
	v_add_f32_e32 v150, v150, v159
	v_add_f32_e32 v150, v150, v160
	v_add_f32_e32 v150, v150, v161
	v_add_f32_e32 v150, v150, v162
	v_add_f32_e32 v150, v150, v163
	v_add_f32_e32 v150, v150, v164
	v_add_f32_e32 v150, v150, v165
	global_store_dword v198, v150, s[94:95]
	s_mov_b64 exec, s[96:97]

; DI unsigned pack2(float a, float b) { fv2 v = {a, b}; return __builtin_bit_cast(unsigned, __builtin_convertvector(v, bfv2)); }
; DI void rmsnorm_rows(const float* x, const float* g, bf16_t* outb, float* outf) {
;     ...
;     for (int rr = 0; rr < 2; ++rr) {
;       const int row = it * 16 + rr * 8 + w;
;       const float rs = rsqrtf(ss[rr] * (1.f / 1024.f) + 1e-6f);
; #pragma unroll
;       for (int i = 0; i < 4; ++i) {
;         const float o0 = v[rr][i].x * rs * gg[i].x, o1 = v[rr][i].y * rs * gg[i].y, o2 = v[rr][i].z * rs * gg[i].z, o3 = v[rr][i].w * rs * gg[i].w;
;         if (outf) { *(float4*)(outf + (size_t)row * 1024 + lane * 4 + 256 * i) = make_float4(o0, o1, o2, o3); }
;         else { uint2 o; o.x = pack2(o0, o1); o.y = pack2(o2, o3); *(uint2*)(outb + (size_t)row * 1024 + lane * 4 + 256 * i) = o; }
;       }
.LBB0_1087:
	v_readlane_b32 s0, v252, 6
	v_readlane_b32 s1, v252, 7
	s_load_dwordx2 s[2:3], s[0:1], 0xe8
	s_load_dwordx2 s[4:5], s[0:1], 0xe0
	s_load_dwordx2 s[6:7], s[0:1], 0xf0
	v_lshrrev_b32_e32 v191, 6, v201
	v_lshrrev_b32_e32 v192, 2, v191
	v_and_b32_e32 v193, 3, v191
	v_and_b32_e32 v194, 15, v201
	v_bfe_u32 v195, v201, 4, 2
	v_lshlrev_b32_e32 v190, 18, v192
	v_lshl_or_b32 v190, v194, 12, v190
	v_lshl_or_b32 v190, v193, 7, v190
	v_lshl_or_b32 v190, v195, 4, v190
	v_lshlrev_b32_e32 v198, 2, v201
	v_mov_b32_e32 v161, 0x358637bd
	s_mov_b32 s10, 0x800000
	s_waitcnt lgkmcnt(0)
	s_lshl_b32 s11, s90, 10
	s_add_u32 s6, s6, 0xaaa4500
	s_addc_u32 s7, s7, 0
	s_add_u32 s6, s6, s11
	s_addc_u32 s7, s7, 0
	s_lshl_b32 s11, s91, 10
	s_add_u32 s4, s4, s11
	s_addc_u32 s5, s5, 0
	v_lshlrev_b32_e32 v199, 7, v193
	v_lshl_or_b32 v199, v195, 4, v199
	global_load_dwordx4 v[162:165], v199, s[4:5]
	global_load_dwordx4 v[166:169], v199, s[4:5] offset:64
	global_load_dwordx4 v[170:173], v199, s[4:5] offset:512
	global_load_dwordx4 v[174:177], v199, s[4:5] offset:576
	v_cmp_gt_u32_e32 vcc, 0x100, v201
	s_and_saveexec_b64 s[96:97], vcc
	global_load_dword v150, v198, s[6:7]
	s_add_u32 s6, s6, 0x10000
	s_addc_u32 s7, s7, 0
	global_load_dword v151, v198, s[6:7]
	s_add_u32 s6, s6, 0x10000
	s_addc_u32 s7, s7, 0
	global_load_dword v152, v198, s[6:7]
	s_add_u32 s6, s6, 0x10000
	s_addc_u32 s7, s7, 0
	global_load_dword v153, v198, s[6:7]
	s_waitcnt vmcnt(0)
	v_add_f32_e32 v150, v150, v151
	v_add_f32_e32 v150, v150, v152
	v_add_f32_e32 v150, v150, v153
	v_fmamk_f32 v160, v150, 0x3a800000, v161
	v_mul_f32_e32 v154, 0x4b800000, v160
	v_cmp_gt_f32_e64 s[8:9], s10, v160
	s_nop 1
	v_cndmask_b32_e64 v160, v160, v154, s[8:9]
	v_rsq_f32_e32 v160, v160
	s_nop 0
	v_mul_f32_e32 v154, 0x45800000, v160
	v_cndmask_b32_e64 v160, v160, v154, s[8:9]
	v_add_u32_e32 v155, 0x20000, v198
	ds_write_b32 v155, v160
	s_mov_b64 exec, s[96:97]
	s_waitcnt vmcnt(0) lgkmcnt(0)
	s_barrier
	v_lshl_or_b32 v196, v192, 6, v194
	v_lshlrev_b32_e32 v196, 2, v196
	v_add_u32_e32 v196, 0x20000, v196
	ds_read_b32 v182, v196
	ds_read_b32 v183, v196 offset:64
	ds_read_b32 v184, v196 offset:128
	ds_read_b32 v185, v196 offset:192
	ds_read_b32 v186, v196 offset:512
	ds_read_b32 v187, v196 offset:576
	ds_read_b32 v188, v196 offset:640
	ds_read_b32 v189, v196 offset:704
	s_lshl_b32 s100, s90, 20
	s_lshl_b32 s101, s91, 10
	s_add_u32 s100, s100, s101
	s_add_u32 s100, s2, s100
	s_addc_u32 s101, s3, 0
	s_waitcnt lgkmcnt(0)
	s_add_u32 s96, s100, 0x0
	s_addc_u32 s97, s101, 0
	v_pk_mul_f32 v[126:127], v[126:127], v[182:183] op_sel_hi:[1,0]
	v_pk_mul_f32 v[128:129], v[128:129], v[182:183] op_sel_hi:[1,0]
	v_pk_mul_f32 v[126:127], v[162:163], v[126:127]
	v_pk_mul_f32 v[128:129], v[164:165], v[128:129]
	global_store_dwordx4 v190, v[126:129], s[96:97]
	v_pk_mul_f32 v[122:123], v[122:123], v[182:183] op_sel_hi:[1,0]
	v_pk_mul_f32 v[124:125], v[124:125], v[182:183] op_sel_hi:[1,0]
	v_pk_mul_f32 v[122:123], v[166:167], v[122:123]
	v_pk_mul_f32 v[124:125], v[168:169], v[124:125]
	global_store_dwordx4 v190, v[122:125], s[96:97] offset:64
	v_pk_mul_f32 v[110:111], v[110:111], v[182:183] op_sel_hi:[1,0]
	v_pk_mul_f32 v[112:113], v[112:113], v[182:183] op_sel_hi:[1,0]
	v_pk_mul_f32 v[110:111], v[170:171], v[110:111]
	v_pk_mul_f32 v[112:113], v[172:173], v[112:113]
	global_store_dwordx4 v190, v[110:113], s[96:97] offset:512
	v_pk_mul_f32 v[106:107], v[106:107], v[182:183] op_sel_hi:[1,0]
	v_pk_mul_f32 v[108:109], v[108:109], v[182:183] op_sel_hi:[1,0]
	v_pk_mul_f32 v[106:107], v[174:175], v[106:107]
	v_pk_mul_f32 v[108:109], v[176:177], v[108:109]
	global_store_dwordx4 v190, v[106:109], s[96:97] offset:576
	s_add_u32 s96, s100, 0x10000
	s_addc_u32 s97, s101, 0
	v_pk_mul_f32 v[118:119], v[118:119], v[182:183] op_sel:[0,1] op_sel_hi:[1,1]
	v_pk_mul_f32 v[120:121], v[120:121], v[182:183] op_sel:[0,1] op_sel_hi:[1,1]
	v_pk_mul_f32 v[118:119], v[162:163], v[118:119]
	v_pk_mul_f32 v[120:121], v[164:165], v[120:121]
	global_store_dwordx4 v190, v[118:121], s[96:97]
	v_pk_mul_f32 v[114:115], v[114:115], v[182:183] op_sel:[0,1] op_sel_hi:[1,1]
	v_pk_mul_f32 v[116:117], v[116:117], v[182:183] op_sel:[0,1] op_sel_hi:[1,1]
	v_pk_mul_f32 v[114:115], v[166:167], v[114:115]
	v_pk_mul_f32 v[116:117], v[168:169], v[116:117]
	global_store_dwordx4 v190, v[114:117], s[96:97] offset:64
	v_pk_mul_f32 v[102:103], v[102:103], v[182:183] op_sel:[0,1] op_sel_hi:[1,1]
	v_pk_mul_f32 v[104:105], v[104:105], v[182:183] op_sel:[0,1] op_sel_hi:[1,1]
	v_pk_mul_f32 v[102:103], v[170:171], v[102:103]
	v_pk_mul_f32 v[104:105], v[172:173], v[104:105]
	global_store_dwordx4 v190, v[102:105], s[96:97] offset:512
	v_pk_mul_f32 v[98:99], v[98:99], v[182:183] op_sel:[0,1] op_sel_hi:[1,1]
	v_pk_mul_f32 v[100:101], v[100:101], v[182:183] op_sel:[0,1] op_sel_hi:[1,1]
	v_pk_mul_f32 v[98:99], v[174:175], v[98:99]
	v_pk_mul_f32 v[100:101], v[176:177], v[100:101]
	global_store_dwordx4 v190, v[98:101], s[96:97] offset:576
	s_add_u32 s96, s100, 0x20000
	s_addc_u32 s97, s101, 0
	v_pk_mul_f32 v[94:95], v[94:95], v[184:185] op_sel_hi:[1,0]
	v_pk_mul_f32 v[96:97], v[96:97], v[184:185] op_sel_hi:[1,0]
	v_pk_mul_f32 v[94:95], v[162:163], v[94:95]
	v_pk_mul_f32 v[96:97], v[164:165], v[96:97]
	global_store_dwordx4 v190, v[94:97], s[96:97]
	v_pk_mul_f32 v[90:91], v[90:91], v[184:185] op_sel_hi:[1,0]
	v_pk_mul_f32 v[92:93], v[92:93], v[184:185] op_sel_hi:[1,0]
	v_pk_mul_f32 v[90:91], v[166:167], v[90:91]
	v_pk_mul_f32 v[92:93], v[168:169], v[92:93]
	global_store_dwordx4 v190, v[90:93], s[96:97] offset:64
	v_pk_mul_f32 v[78:79], v[78:79], v[184:185] op_sel_hi:[1,0]
	v_pk_mul_f32 v[80:81], v[80:81], v[184:185] op_sel_hi:[1,0]
; DI unsigned pack2(float a, float b) { fv2 v = {a, b}; return __builtin_bit_cast(unsigned, __builtin_convertvector(v, bfv2)); }
; DI void rmsnorm_rows(const float* x, const float* g, bf16_t* outb, float* outf) {
;     ...
; #pragma unroll
;       for (int i = 0; i < 4; ++i) {
;         const float o0 = v[rr][i].x * rs * gg[i].x, o1 = v[rr][i].y * rs * gg[i].y, o2 = v[rr][i].z * rs * gg[i].z, o3 = v[rr][i].w * rs * gg[i].w;
;         if (outf) { *(float4*)(outf + (size_t)row * 1024 + lane * 4 + 256 * i) = make_float4(o0, o1, o2, o3); }
;         else { uint2 o; o.x = pack2(o0, o1); o.y = pack2(o2, o3); *(uint2*)(outb + (size_t)row * 1024 + lane * 4 + 256 * i) = o; }
;       }
	v_pk_mul_f32 v[78:79], v[170:171], v[78:79]
	v_pk_mul_f32 v[80:81], v[172:173], v[80:81]
	global_store_dwordx4 v190, v[78:81], s[96:97] offset:512
	v_pk_mul_f32 v[74:75], v[74:75], v[184:185] op_sel_hi:[1,0]
	v_pk_mul_f32 v[76:77], v[76:77], v[184:185] op_sel_hi:[1,0]
	v_pk_mul_f32 v[74:75], v[174:175], v[74:75]
	v_pk_mul_f32 v[76:77], v[176:177], v[76:77]
	global_store_dwordx4 v190, v[74:77], s[96:97] offset:576
	s_add_u32 s96, s100, 0x30000
	s_addc_u32 s97, s101, 0
	v_pk_mul_f32 v[86:87], v[86:87], v[184:185] op_sel:[0,1] op_sel_hi:[1,1]
	v_pk_mul_f32 v[88:89], v[88:89], v[184:185] op_sel:[0,1] op_sel_hi:[1,1]
	v_pk_mul_f32 v[86:87], v[162:163], v[86:87]
	v_pk_mul_f32 v[88:89], v[164:165], v[88:89]
	global_store_dwordx4 v190, v[86:89], s[96:97]
	v_pk_mul_f32 v[82:83], v[82:83], v[184:185] op_sel:[0,1] op_sel_hi:[1,1]
	v_pk_mul_f32 v[84:85], v[84:85], v[184:185] op_sel:[0,1] op_sel_hi:[1,1]
	v_pk_mul_f32 v[82:83], v[166:167], v[82:83]
	v_pk_mul_f32 v[84:85], v[168:169], v[84:85]
	global_store_dwordx4 v190, v[82:85], s[96:97] offset:64
	v_pk_mul_f32 v[70:71], v[70:71], v[184:185] op_sel:[0,1] op_sel_hi:[1,1]
	v_pk_mul_f32 v[72:73], v[72:73], v[184:185] op_sel:[0,1] op_sel_hi:[1,1]
	v_pk_mul_f32 v[70:71], v[170:171], v[70:71]
	v_pk_mul_f32 v[72:73], v[172:173], v[72:73]
	global_store_dwordx4 v190, v[70:73], s[96:97] offset:512
	v_pk_mul_f32 v[66:67], v[66:67], v[184:185] op_sel:[0,1] op_sel_hi:[1,1]
	v_pk_mul_f32 v[68:69], v[68:69], v[184:185] op_sel:[0,1] op_sel_hi:[1,1]
	v_pk_mul_f32 v[66:67], v[174:175], v[66:67]
	v_pk_mul_f32 v[68:69], v[176:177], v[68:69]
	global_store_dwordx4 v190, v[66:69], s[96:97] offset:576
	s_add_u32 s96, s100, 0x80000
	s_addc_u32 s97, s101, 0
	v_pk_mul_f32 v[62:63], v[62:63], v[186:187] op_sel_hi:[1,0]
	v_pk_mul_f32 v[64:65], v[64:65], v[186:187] op_sel_hi:[1,0]
	v_pk_mul_f32 v[62:63], v[162:163], v[62:63]
	v_pk_mul_f32 v[64:65], v[164:165], v[64:65]
	global_store_dwordx4 v190, v[62:65], s[96:97]
	v_pk_mul_f32 v[58:59], v[58:59], v[186:187] op_sel_hi:[1,0]
	v_pk_mul_f32 v[60:61], v[60:61], v[186:187] op_sel_hi:[1,0]
	v_pk_mul_f32 v[58:59], v[166:167], v[58:59]
	v_pk_mul_f32 v[60:61], v[168:169], v[60:61]
	global_store_dwordx4 v190, v[58:61], s[96:97] offset:64
	v_pk_mul_f32 v[46:47], v[46:47], v[186:187] op_sel_hi:[1,0]
	v_pk_mul_f32 v[48:49], v[48:49], v[186:187] op_sel_hi:[1,0]
	v_pk_mul_f32 v[46:47], v[170:171], v[46:47]
	v_pk_mul_f32 v[48:49], v[172:173], v[48:49]
	global_store_dwordx4 v190, v[46:49], s[96:97] offset:512
	v_pk_mul_f32 v[42:43], v[42:43], v[186:187] op_sel_hi:[1,0]
	v_pk_mul_f32 v[44:45], v[44:45], v[186:187] op_sel_hi:[1,0]
	v_pk_mul_f32 v[42:43], v[174:175], v[42:43]
	v_pk_mul_f32 v[44:45], v[176:177], v[44:45]
	global_store_dwordx4 v190, v[42:45], s[96:97] offset:576
	s_add_u32 s96, s100, 0x90000
	s_addc_u32 s97, s101, 0
	v_pk_mul_f32 v[54:55], v[54:55], v[186:187] op_sel:[0,1] op_sel_hi:[1,1]
	v_pk_mul_f32 v[56:57], v[56:57], v[186:187] op_sel:[0,1] op_sel_hi:[1,1]
	v_pk_mul_f32 v[54:55], v[162:163], v[54:55]
	v_pk_mul_f32 v[56:57], v[164:165], v[56:57]
	global_store_dwordx4 v190, v[54:57], s[96:97]
	v_pk_mul_f32 v[50:51], v[50:51], v[186:187] op_sel:[0,1] op_sel_hi:[1,1]
	v_pk_mul_f32 v[52:53], v[52:53], v[186:187] op_sel:[0,1] op_sel_hi:[1,1]
	v_pk_mul_f32 v[50:51], v[166:167], v[50:51]
	v_pk_mul_f32 v[52:53], v[168:169], v[52:53]
	global_store_dwordx4 v190, v[50:53], s[96:97] offset:64
	v_pk_mul_f32 v[38:39], v[38:39], v[186:187] op_sel:[0,1] op_sel_hi:[1,1]
	v_pk_mul_f32 v[40:41], v[40:41], v[186:187] op_sel:[0,1] op_sel_hi:[1,1]
	v_pk_mul_f32 v[38:39], v[170:171], v[38:39]
	v_pk_mul_f32 v[40:41], v[172:173], v[40:41]
	global_store_dwordx4 v190, v[38:41], s[96:97] offset:512
	v_pk_mul_f32 v[34:35], v[34:35], v[186:187] op_sel:[0,1] op_sel_hi:[1,1]
	v_pk_mul_f32 v[36:37], v[36:37], v[186:187] op_sel:[0,1] op_sel_hi:[1,1]
	v_pk_mul_f32 v[34:35], v[174:175], v[34:35]
	v_pk_mul_f32 v[36:37], v[176:177], v[36:37]
	global_store_dwordx4 v190, v[34:37], s[96:97] offset:576
	s_add_u32 s96, s100, 0xa0000
	s_addc_u32 s97, s101, 0
	v_pk_mul_f32 v[30:31], v[30:31], v[188:189] op_sel_hi:[1,0]
	v_pk_mul_f32 v[32:33], v[32:33], v[188:189] op_sel_hi:[1,0]
	v_pk_mul_f32 v[30:31], v[162:163], v[30:31]
	v_pk_mul_f32 v[32:33], v[164:165], v[32:33]
	global_store_dwordx4 v190, v[30:33], s[96:97]
	v_pk_mul_f32 v[26:27], v[26:27], v[188:189] op_sel_hi:[1,0]
	v_pk_mul_f32 v[28:29], v[28:29], v[188:189] op_sel_hi:[1,0]
	v_pk_mul_f32 v[26:27], v[166:167], v[26:27]
	v_pk_mul_f32 v[28:29], v[168:169], v[28:29]
	global_store_dwordx4 v190, v[26:29], s[96:97] offset:64
	v_pk_mul_f32 v[134:135], v[134:135], v[188:189] op_sel_hi:[1,0]
	v_pk_mul_f32 v[136:137], v[136:137], v[188:189] op_sel_hi:[1,0]
	v_pk_mul_f32 v[134:135], v[170:171], v[134:135]
	v_pk_mul_f32 v[136:137], v[172:173], v[136:137]
	global_store_dwordx4 v190, v[134:137], s[96:97] offset:512
	v_pk_mul_f32 v[138:139], v[138:139], v[188:189] op_sel_hi:[1,0]
	v_pk_mul_f32 v[140:141], v[140:141], v[188:189] op_sel_hi:[1,0]
	v_pk_mul_f32 v[138:139], v[174:175], v[138:139]
	v_pk_mul_f32 v[140:141], v[176:177], v[140:141]
	global_store_dwordx4 v190, v[138:141], s[96:97] offset:576
	s_add_u32 s96, s100, 0xb0000
	s_addc_u32 s97, s101, 0
	v_pk_mul_f32 v[22:23], v[22:23], v[188:189] op_sel:[0,1] op_sel_hi:[1,1]
	v_pk_mul_f32 v[24:25], v[24:25], v[188:189] op_sel:[0,1] op_sel_hi:[1,1]
	v_pk_mul_f32 v[22:23], v[162:163], v[22:23]
	v_pk_mul_f32 v[24:25], v[164:165], v[24:25]
	global_store_dwordx4 v190, v[22:25], s[96:97]
	v_pk_mul_f32 v[130:131], v[130:131], v[188:189] op_sel:[0,1] op_sel_hi:[1,1]
	v_pk_mul_f32 v[132:133], v[132:133], v[188:189] op_sel:[0,1] op_sel_hi:[1,1]
	v_pk_mul_f32 v[130:131], v[166:167], v[130:131]
	v_pk_mul_f32 v[132:133], v[168:169], v[132:133]
	global_store_dwordx4 v190, v[130:133], s[96:97] offset:64
	v_pk_mul_f32 v[142:143], v[142:143], v[188:189] op_sel:[0,1] op_sel_hi:[1,1]
	v_pk_mul_f32 v[144:145], v[144:145], v[188:189] op_sel:[0,1] op_sel_hi:[1,1]
	v_pk_mul_f32 v[142:143], v[170:171], v[142:143]
	v_pk_mul_f32 v[144:145], v[172:173], v[144:145]
	global_store_dwordx4 v190, v[142:145], s[96:97] offset:512
	v_pk_mul_f32 v[146:147], v[146:147], v[188:189] op_sel:[0,1] op_sel_hi:[1,1]
	v_pk_mul_f32 v[148:149], v[148:149], v[188:189] op_sel:[0,1] op_sel_hi:[1,1]
	v_pk_mul_f32 v[146:147], v[174:175], v[146:147]
	v_pk_mul_f32 v[148:149], v[176:177], v[148:149]
	global_store_dwordx4 v190, v[146:149], s[96:97] offset:576
	s_branch .LBB0_1123
; DI float wave_sum_fast(float v) { v = fdpp_add(v, 0); v = fdpp_add(v, 1); v = fdpp_add(v, 2); v = fdpp_add(v, 3); v = xor16_sum(v); return xor32_sum(v); }
; DI void rmsnorm_rows(const float* x, const float* g, bf16_t* outb, float* outf) {
;     ...
;     for (int rr = 0; rr < 2; ++rr) {
; #pragma unroll
;       for (int i = 0; i < 4; ++i) ss[rr] += v[rr][i].x * v[rr][i].x + v[rr][i].y * v[rr][i].y + v[rr][i].z * v[rr][i].z + v[rr][i].w * v[rr][i].w;
;       ss[rr] = wave_sum_fast(ss[rr]);
;   DI void operator()(const f32x4 (&acc)[2][2][4][2], const Unit& u, int wr, int wc, int fr, int fq) const {
;     const int row0 = u.pm * BM + wr * 64 + fr, col0 = u.pn * BM + wc * 32 + 4 * fq;
; #pragma unroll
;     for (int ai = 0; ai < 2; ++ai)
; #pragma unroll
;       for (int mp = 0; mp < 2; ++mp) {
;         f32x4 xv[2][2][2];
; #pragma unroll
;         for (int mm = 0; mm < 2; ++mm)
; #pragma unroll
;           for (int bj = 0; bj < 2; ++bj)
; #pragma unroll
;             for (int n = 0; n < 2; ++n)
;               xv[mm][bj][n] = *(const f32x4*)(X + (size_t)(row0 + ai * HALF + (mp * 2 + mm) * 16) * 1024 + col0 + bj * HALF + n * 16);
; #pragma unroll
;         for (int mm = 0; mm < 2; ++mm)
; #pragma unroll
;           for (int bj = 0; bj < 2; ++bj)
; #pragma unroll
;             for (int n = 0; n < 2; ++n)
;               *(f32x4*)(O + (size_t)(row0 + ai * HALF + (mp * 2 + mm) * 16) * 1024 + col0 + bj * HALF + n * 16) = xv[mm][bj][n] + acc[ai][bj][mp * 2 + mm][n];
;       }
;   }
.Lfz_p1:
	s_mov_b32 s92, 1
	s_mov_b32 s90, s40
	s_mov_b32 s91, s41
	v_lshrrev_b32_e32 v191, 6, v201
	v_lshrrev_b32_e32 v192, 2, v191
	v_and_b32_e32 v193, 3, v191
	v_and_b32_e32 v194, 15, v201
	v_bfe_u32 v195, v201, 4, 2
	v_lshlrev_b32_e32 v190, 18, v192
	v_lshl_or_b32 v190, v194, 12, v190
	v_lshl_or_b32 v190, v193, 7, v190
	v_lshl_or_b32 v190, v195, 4, v190
	s_lshl_b32 s100, s40, 20
	s_lshl_b32 s101, s41, 10
	s_add_u32 s100, s100, s101
	s_add_u32 s100, s2, s100
	s_addc_u32 s101, s3, 0
	s_add_u32 s96, s100, 0x0
	s_addc_u32 s97, s101, 0
	global_load_dwordx4 v[150:153], v190, s[96:97]
	global_load_dwordx4 v[154:157], v190, s[96:97] offset:64
	global_load_dwordx4 v[158:161], v190, s[96:97] offset:512
	global_load_dwordx4 v[162:165], v190, s[96:97] offset:576
	s_add_u32 s96, s100, 0x10000
	s_addc_u32 s97, s101, 0
	global_load_dwordx4 v[166:169], v190, s[96:97]
	global_load_dwordx4 v[170:173], v190, s[96:97] offset:64
	global_load_dwordx4 v[174:177], v190, s[96:97] offset:512
	global_load_dwordx4 v[178:181], v190, s[96:97] offset:576
	s_waitcnt vmcnt(0)
	v_pk_add_f32 v[126:127], v[126:127], v[150:151]
	v_pk_add_f32 v[128:129], v[128:129], v[152:153]
	v_pk_add_f32 v[122:123], v[122:123], v[154:155]
	v_pk_add_f32 v[124:125], v[124:125], v[156:157]
	v_pk_add_f32 v[110:111], v[110:111], v[158:159]
	v_pk_add_f32 v[112:113], v[112:113], v[160:161]
	v_pk_add_f32 v[106:107], v[106:107], v[162:163]
	v_pk_add_f32 v[108:109], v[108:109], v[164:165]
	v_pk_add_f32 v[118:119], v[118:119], v[166:167]
	v_pk_add_f32 v[120:121], v[120:121], v[168:169]
	v_pk_add_f32 v[114:115], v[114:115], v[170:171]
	v_pk_add_f32 v[116:117], v[116:117], v[172:173]
	v_pk_add_f32 v[102:103], v[102:103], v[174:175]
	v_pk_add_f32 v[104:105], v[104:105], v[176:177]
	v_pk_add_f32 v[98:99], v[98:99], v[178:179]
	v_pk_add_f32 v[100:101], v[100:101], v[180:181]
	s_nop 0
	s_add_u32 s96, s100, 0x20000
	s_addc_u32 s97, s101, 0
	global_load_dwordx4 v[150:153], v190, s[96:97]
	global_load_dwordx4 v[154:157], v190, s[96:97] offset:64
	global_load_dwordx4 v[158:161], v190, s[96:97] offset:512
	global_load_dwordx4 v[162:165], v190, s[96:97] offset:576
	s_add_u32 s96, s100, 0x30000
	s_addc_u32 s97, s101, 0
	global_load_dwordx4 v[166:169], v190, s[96:97]
	global_load_dwordx4 v[170:173], v190, s[96:97] offset:64
	global_load_dwordx4 v[174:177], v190, s[96:97] offset:512
	global_load_dwordx4 v[178:181], v190, s[96:97] offset:576
	v_pk_mul_f32 v[196:197], v[126:127], v[126:127]
	v_pk_fma_f32 v[196:197], v[128:129], v[128:129], v[196:197]
	v_pk_fma_f32 v[196:197], v[122:123], v[122:123], v[196:197]
	v_pk_fma_f32 v[196:197], v[124:125], v[124:125], v[196:197]
	v_pk_fma_f32 v[196:197], v[110:111], v[110:111], v[196:197]
	v_pk_fma_f32 v[196:197], v[112:113], v[112:113], v[196:197]
	v_pk_fma_f32 v[196:197], v[106:107], v[106:107], v[196:197]
	v_pk_fma_f32 v[196:197], v[108:109], v[108:109], v[196:197]
	s_nop 0
	v_add_f32_e32 v182, v196, v197
	v_pk_mul_f32 v[196:197], v[118:119], v[118:119]
	v_pk_fma_f32 v[196:197], v[120:121], v[120:121], v[196:197]
	v_pk_fma_f32 v[196:197], v[114:115], v[114:115], v[196:197]
	v_pk_fma_f32 v[196:197], v[116:117], v[116:117], v[196:197]
	v_pk_fma_f32 v[196:197], v[102:103], v[102:103], v[196:197]
	v_pk_fma_f32 v[196:197], v[104:105], v[104:105], v[196:197]
	v_pk_fma_f32 v[196:197], v[98:99], v[98:99], v[196:197]
	v_pk_fma_f32 v[196:197], v[100:101], v[100:101], v[196:197]
	s_nop 0
	v_add_f32_e32 v183, v196, v197
	s_waitcnt vmcnt(0)
	v_pk_add_f32 v[94:95], v[94:95], v[150:151]
	v_pk_add_f32 v[96:97], v[96:97], v[152:153]
	v_pk_add_f32 v[90:91], v[90:91], v[154:155]
	v_pk_add_f32 v[92:93], v[92:93], v[156:157]
	v_pk_add_f32 v[78:79], v[78:79], v[158:159]
	v_pk_add_f32 v[80:81], v[80:81], v[160:161]
	v_pk_add_f32 v[74:75], v[74:75], v[162:163]
	v_pk_add_f32 v[76:77], v[76:77], v[164:165]
	v_pk_add_f32 v[86:87], v[86:87], v[166:167]
	v_pk_add_f32 v[88:89], v[88:89], v[168:169]
	v_pk_add_f32 v[82:83], v[82:83], v[170:171]
	v_pk_add_f32 v[84:85], v[84:85], v[172:173]
	v_pk_add_f32 v[70:71], v[70:71], v[174:175]
	v_pk_add_f32 v[72:73], v[72:73], v[176:177]
	v_pk_add_f32 v[66:67], v[66:67], v[178:179]
	v_pk_add_f32 v[68:69], v[68:69], v[180:181]
	s_nop 0
	s_add_u32 s96, s100, 0x80000
	s_addc_u32 s97, s101, 0
	global_load_dwordx4 v[150:153], v190, s[96:97]
	global_load_dwordx4 v[154:157], v190, s[96:97] offset:64
	global_load_dwordx4 v[158:161], v190, s[96:97] offset:512
	global_load_dwordx4 v[162:165], v190, s[96:97] offset:576
	s_add_u32 s96, s100, 0x90000
	s_addc_u32 s97, s101, 0
	global_load_dwordx4 v[166:169], v190, s[96:97]
	global_load_dwordx4 v[170:173], v190, s[96:97] offset:64
	global_load_dwordx4 v[174:177], v190, s[96:97] offset:512
	global_load_dwordx4 v[178:181], v190, s[96:97] offset:576
	v_pk_mul_f32 v[196:197], v[94:95], v[94:95]
	v_pk_fma_f32 v[196:197], v[96:97], v[96:97], v[196:197]
	v_pk_fma_f32 v[196:197], v[90:91], v[90:91], v[196:197]
	v_pk_fma_f32 v[196:197], v[92:93], v[92:93], v[196:197]
	v_pk_fma_f32 v[196:197], v[78:79], v[78:79], v[196:197]
	v_pk_fma_f32 v[196:197], v[80:81], v[80:81], v[196:197]
	v_pk_fma_f32 v[196:197], v[74:75], v[74:75], v[196:197]
	v_pk_fma_f32 v[196:197], v[76:77], v[76:77], v[196:197]
	s_nop 0
	v_add_f32_e32 v184, v196, v197
	v_pk_mul_f32 v[196:197], v[86:87], v[86:87]
	v_pk_fma_f32 v[196:197], v[88:89], v[88:89], v[196:197]
	v_pk_fma_f32 v[196:197], v[82:83], v[82:83], v[196:197]
	v_pk_fma_f32 v[196:197], v[84:85], v[84:85], v[196:197]
	v_pk_fma_f32 v[196:197], v[70:71], v[70:71], v[196:197]
	v_pk_fma_f32 v[196:197], v[72:73], v[72:73], v[196:197]
	v_pk_fma_f32 v[196:197], v[66:67], v[66:67], v[196:197]
	v_pk_fma_f32 v[196:197], v[68:69], v[68:69], v[196:197]
	s_nop 0
	v_add_f32_e32 v185, v196, v197
	s_waitcnt vmcnt(0)
; DI void rmsnorm_rows(const float* x, const float* g, bf16_t* outb, float* outf) {
;     ...
;       for (int i = 0; i < 4; ++i) ss[rr] += v[rr][i].x * v[rr][i].x + v[rr][i].y * v[rr][i].y + v[rr][i].z * v[rr][i].z + v[rr][i].w * v[rr][i].w;
;   DI void operator()(const f32x4 (&acc)[2][2][4][2], const Unit& u, int wr, int wc, int fr, int fq) const {
;     const int row0 = u.pm * BM + wr * 64 + fr, col0 = u.pn * BM + wc * 32 + 4 * fq;
; #pragma unroll
;     for (int ai = 0; ai < 2; ++ai)
; #pragma unroll
;       for (int mp = 0; mp < 2; ++mp) {
;         f32x4 xv[2][2][2];
; #pragma unroll
;         for (int mm = 0; mm < 2; ++mm)
; #pragma unroll
;           for (int bj = 0; bj < 2; ++bj)
; #pragma unroll
;             for (int n = 0; n < 2; ++n)
;               xv[mm][bj][n] = *(const f32x4*)(X + (size_t)(row0 + ai * HALF + (mp * 2 + mm) * 16) * 1024 + col0 + bj * HALF + n * 16);
; #pragma unroll
;         for (int mm = 0; mm < 2; ++mm)
; #pragma unroll
;           for (int bj = 0; bj < 2; ++bj)
; #pragma unroll
;             for (int n = 0; n < 2; ++n)
;               *(f32x4*)(O + (size_t)(row0 + ai * HALF + (mp * 2 + mm) * 16) * 1024 + col0 + bj * HALF + n * 16) = xv[mm][bj][n] + acc[ai][bj][mp * 2 + mm][n];
;       }
;   }
	v_pk_add_f32 v[62:63], v[62:63], v[150:151]
	v_pk_add_f32 v[64:65], v[64:65], v[152:153]
	v_pk_add_f32 v[58:59], v[58:59], v[154:155]
	v_pk_add_f32 v[60:61], v[60:61], v[156:157]
	v_pk_add_f32 v[46:47], v[46:47], v[158:159]
	v_pk_add_f32 v[48:49], v[48:49], v[160:161]
	v_pk_add_f32 v[42:43], v[42:43], v[162:163]
	v_pk_add_f32 v[44:45], v[44:45], v[164:165]
	v_pk_add_f32 v[54:55], v[54:55], v[166:167]
	v_pk_add_f32 v[56:57], v[56:57], v[168:169]
	v_pk_add_f32 v[50:51], v[50:51], v[170:171]
	v_pk_add_f32 v[52:53], v[52:53], v[172:173]
	v_pk_add_f32 v[38:39], v[38:39], v[174:175]
	v_pk_add_f32 v[40:41], v[40:41], v[176:177]
	v_pk_add_f32 v[34:35], v[34:35], v[178:179]
	v_pk_add_f32 v[36:37], v[36:37], v[180:181]
	s_nop 0
	s_add_u32 s96, s100, 0xa0000
	s_addc_u32 s97, s101, 0
	global_load_dwordx4 v[150:153], v190, s[96:97]
	global_load_dwordx4 v[154:157], v190, s[96:97] offset:64
	global_load_dwordx4 v[158:161], v190, s[96:97] offset:512
	global_load_dwordx4 v[162:165], v190, s[96:97] offset:576
	s_add_u32 s96, s100, 0xb0000
	s_addc_u32 s97, s101, 0
	global_load_dwordx4 v[166:169], v190, s[96:97]
	global_load_dwordx4 v[170:173], v190, s[96:97] offset:64
	global_load_dwordx4 v[174:177], v190, s[96:97] offset:512
	global_load_dwordx4 v[178:181], v190, s[96:97] offset:576
	v_pk_mul_f32 v[196:197], v[62:63], v[62:63]
	v_pk_fma_f32 v[196:197], v[64:65], v[64:65], v[196:197]
	v_pk_fma_f32 v[196:197], v[58:59], v[58:59], v[196:197]
	v_pk_fma_f32 v[196:197], v[60:61], v[60:61], v[196:197]
	v_pk_fma_f32 v[196:197], v[46:47], v[46:47], v[196:197]
	v_pk_fma_f32 v[196:197], v[48:49], v[48:49], v[196:197]
	v_pk_fma_f32 v[196:197], v[42:43], v[42:43], v[196:197]
	v_pk_fma_f32 v[196:197], v[44:45], v[44:45], v[196:197]
	s_nop 0
	v_add_f32_e32 v186, v196, v197
	v_pk_mul_f32 v[196:197], v[54:55], v[54:55]
	v_pk_fma_f32 v[196:197], v[56:57], v[56:57], v[196:197]
	v_pk_fma_f32 v[196:197], v[50:51], v[50:51], v[196:197]
	v_pk_fma_f32 v[196:197], v[52:53], v[52:53], v[196:197]
	v_pk_fma_f32 v[196:197], v[38:39], v[38:39], v[196:197]
	v_pk_fma_f32 v[196:197], v[40:41], v[40:41], v[196:197]
	v_pk_fma_f32 v[196:197], v[34:35], v[34:35], v[196:197]
	v_pk_fma_f32 v[196:197], v[36:37], v[36:37], v[196:197]
	s_nop 0
	v_add_f32_e32 v187, v196, v197
	s_waitcnt vmcnt(0)
	v_pk_add_f32 v[30:31], v[30:31], v[150:151]
	v_pk_add_f32 v[32:33], v[32:33], v[152:153]
	v_pk_add_f32 v[26:27], v[26:27], v[154:155]
	v_pk_add_f32 v[28:29], v[28:29], v[156:157]
	v_pk_add_f32 v[14:15], v[14:15], v[158:159]
	v_pk_add_f32 v[16:17], v[16:17], v[160:161]
	v_pk_add_f32 v[10:11], v[10:11], v[162:163]
	v_pk_add_f32 v[12:13], v[12:13], v[164:165]
	v_pk_add_f32 v[22:23], v[22:23], v[166:167]
	v_pk_add_f32 v[24:25], v[24:25], v[168:169]
	v_pk_add_f32 v[18:19], v[18:19], v[170:171]
	v_pk_add_f32 v[20:21], v[20:21], v[172:173]
	v_pk_add_f32 v[6:7], v[6:7], v[174:175]
	v_pk_add_f32 v[8:9], v[8:9], v[176:177]
	v_pk_add_f32 v[2:3], v[2:3], v[178:179]
	v_pk_add_f32 v[4:5], v[4:5], v[180:181]
	v_pk_mul_f32 v[196:197], v[30:31], v[30:31]
	v_pk_fma_f32 v[196:197], v[32:33], v[32:33], v[196:197]
	v_pk_fma_f32 v[196:197], v[26:27], v[26:27], v[196:197]
	v_pk_fma_f32 v[196:197], v[28:29], v[28:29], v[196:197]
	v_pk_fma_f32 v[196:197], v[14:15], v[14:15], v[196:197]
	v_pk_fma_f32 v[196:197], v[16:17], v[16:17], v[196:197]
	v_pk_fma_f32 v[196:197], v[10:11], v[10:11], v[196:197]
	v_pk_fma_f32 v[196:197], v[12:13], v[12:13], v[196:197]
	s_nop 0
	v_add_f32_e32 v188, v196, v197
	v_pk_mul_f32 v[196:197], v[22:23], v[22:23]
	v_pk_fma_f32 v[196:197], v[24:25], v[24:25], v[196:197]
	v_pk_fma_f32 v[196:197], v[18:19], v[18:19], v[196:197]
	v_pk_fma_f32 v[196:197], v[20:21], v[20:21], v[196:197]
	v_pk_fma_f32 v[196:197], v[6:7], v[6:7], v[196:197]
	v_pk_fma_f32 v[196:197], v[8:9], v[8:9], v[196:197]
	v_pk_fma_f32 v[196:197], v[2:3], v[2:3], v[196:197]
	v_pk_fma_f32 v[196:197], v[4:5], v[4:5], v[196:197]
	s_nop 0
	v_add_f32_e32 v189, v196, v197
	v_mov_b32_e32 v130, v18
	v_mov_b32_e32 v131, v19
	v_mov_b32_e32 v132, v20
	v_mov_b32_e32 v133, v21
	v_mov_b32_e32 v134, v14
	v_mov_b32_e32 v135, v15
	v_mov_b32_e32 v136, v16
	v_mov_b32_e32 v137, v17
	v_mov_b32_e32 v138, v10
	v_mov_b32_e32 v139, v11
	v_mov_b32_e32 v140, v12
	v_mov_b32_e32 v141, v13
	v_mov_b32_e32 v142, v6
	v_mov_b32_e32 v143, v7
	v_mov_b32_e32 v144, v8
	v_mov_b32_e32 v145, v9
	v_mov_b32_e32 v146, v2
	v_mov_b32_e32 v147, v3
	v_mov_b32_e32 v148, v4
	v_mov_b32_e32 v149, v5
	s_and_b64 vcc, exec, s[36:37]
	s_mov_b64 s[42:43], s[38:39]
	s_mov_b64 s[44:45], s[34:35]
	s_branch .Lfz_p1_ret
